# prep_x row quarters and load_u5_tile (M1, s5_pass2) loads issued together instead of one memory round trip each
# speedup vs baseline: 1.0141x; 1.0028x over previous
.LBB0_226:
	v_lshl_add_u64 v[14:15], s[12:13], 0, v[4:5]
	v_add_co_u32_e64 v26, s[4:5], s0, v14
	s_waitcnt lgkmcnt(0)
	s_nop 1
	v_addc_co_u32_e64 v27, s[4:5], 0, v15, s[4:5]
	global_load_dwordx4 v[10:13], v[6:7], off offset:-2048
	global_load_dwordx4 v[14:17], v[6:7], off offset:-1024
	global_load_dwordx4 v[18:21], v[6:7], off
	global_load_dwordx4 v[22:25], v[6:7], off offset:1024
	s_waitcnt vmcnt(3)
	v_cvt_pk_bf16_f32 v230, v10, v11
	v_cvt_pk_bf16_f32 v231, v12, v13
	global_store_dwordx2 v[26:27], v[230:231], off
	s_waitcnt vmcnt(3)
	v_cvt_pk_bf16_f32 v232, v14, v15
	v_cvt_pk_bf16_f32 v233, v16, v17
	global_store_dwordx2 v[26:27], v[232:233], off offset:512
	s_waitcnt vmcnt(3)
	v_cvt_pk_bf16_f32 v234, v18, v19
	v_cvt_pk_bf16_f32 v235, v20, v21
	global_store_dwordx2 v[26:27], v[234:235], off offset:1024
	v_mul_f32_e32 v11, v11, v11
	v_mul_f32_e32 v13, v13, v13
	v_fmac_f32_e32 v11, v10, v10
	v_fmac_f32_e32 v13, v12, v12
	v_add_f32_e32 v10, v11, v13
	v_mul_f32_e32 v11, v15, v15
	v_mul_f32_e32 v12, v17, v17
	v_fmac_f32_e32 v11, v14, v14
	v_fmac_f32_e32 v12, v16, v16
	v_add_f32_e32 v11, v11, v12
	v_add_f32_e32 v10, v10, v11
	v_mul_f32_e32 v11, v19, v19
	v_mul_f32_e32 v12, v21, v21
	v_fmac_f32_e32 v11, v18, v18
	v_fmac_f32_e32 v12, v20, v20
	v_add_f32_e32 v11, v11, v12
	v_add_f32_e32 v10, v10, v11
	s_waitcnt vmcnt(3)
	v_mul_f32_e32 v11, v23, v23
	v_mul_f32_e32 v12, v25, v25
	v_fmac_f32_e32 v11, v22, v22
	v_fmac_f32_e32 v12, v24, v24
	v_add_f32_e32 v11, v11, v12
	v_add_f32_e32 v10, v10, v11
	ds_bpermute_b32 v11, v8, v10
	v_cvt_pk_bf16_f32 v12, v22, v23
	v_cvt_pk_bf16_f32 v13, v24, v25
	global_store_dwordx2 v[26:27], v[12:13], off offset:1536
	s_waitcnt lgkmcnt(0)
	v_add_f32_e32 v10, v10, v11
	ds_bpermute_b32 v11, v9, v10
	s_and_saveexec_b64 s[4:5], vcc
	s_cbranch_execz .LBB0_225
	s_waitcnt lgkmcnt(0)
	v_add_f32_e32 v12, v10, v11
	v_lshl_add_u64 v[10:11], s[12:13], 0, v[2:3]
	global_store_dword v[10:11], v12, off
	s_branch .LBB0_225

.LBB0_494:
	v_ashrrev_i32_e32 v32, 6, v27
	v_add_u32_e32 v28, s18, v32
	v_ashrrev_i32_e32 v29, 31, v28
	v_and_b32_e32 v33, 0xfc, v1
	v_lshlrev_b64 v[28:29], 9, v[28:29]
	v_lshlrev_b32_e32 v4, 1, v33
	v_lshl_add_u64 v[28:29], s[28:29], 0, v[28:29]
	v_lshl_add_u64 v[28:29], v[28:29], 0, v[4:5]
	v_lshlrev_b32_e32 v32, 10, v32
	v_lshlrev_b32_e32 v33, 2, v33
	v_add3_u32 v4, 0, v32, v33
	s_mov_b64 s[12:13], 0x1000
	global_load_dwordx2 v[160:161], v[28:29], off
	v_lshl_add_u64 v[28:29], v[28:29], 0, s[12:13]
	global_load_dwordx2 v[162:163], v[28:29], off
	v_lshl_add_u64 v[28:29], v[28:29], 0, s[12:13]
	global_load_dwordx2 v[164:165], v[28:29], off
	v_lshl_add_u64 v[28:29], v[28:29], 0, s[12:13]
	global_load_dwordx2 v[166:167], v[28:29], off
	v_lshl_add_u64 v[28:29], v[28:29], 0, s[12:13]
	global_load_dwordx2 v[168:169], v[28:29], off
	v_lshl_add_u64 v[28:29], v[28:29], 0, s[12:13]
	global_load_dwordx2 v[170:171], v[28:29], off
	v_lshl_add_u64 v[28:29], v[28:29], 0, s[12:13]
	global_load_dwordx2 v[172:173], v[28:29], off
	v_lshl_add_u64 v[28:29], v[28:29], 0, s[12:13]
	global_load_dwordx2 v[174:175], v[28:29], off
	s_waitcnt vmcnt(7)
	v_cvt_f32_f16_e32 v176, v160
	v_cvt_f32_f16_sdwa v177, v160 dst_sel:DWORD dst_unused:UNUSED_PAD src0_sel:WORD_1
	v_cvt_f32_f16_e32 v178, v161
	v_cvt_f32_f16_sdwa v179, v161 dst_sel:DWORD dst_unused:UNUSED_PAD src0_sel:WORD_1
	ds_write_b128 v4, v[176:179]
	s_waitcnt vmcnt(6)
	v_cvt_f32_f16_e32 v180, v162
	v_cvt_f32_f16_sdwa v181, v162 dst_sel:DWORD dst_unused:UNUSED_PAD src0_sel:WORD_1
	v_cvt_f32_f16_e32 v182, v163
	v_cvt_f32_f16_sdwa v183, v163 dst_sel:DWORD dst_unused:UNUSED_PAD src0_sel:WORD_1
	ds_write_b128 v4, v[180:183] offset:8192
	s_waitcnt vmcnt(5)
	v_cvt_f32_f16_e32 v184, v164
	v_cvt_f32_f16_sdwa v185, v164 dst_sel:DWORD dst_unused:UNUSED_PAD src0_sel:WORD_1
	v_cvt_f32_f16_e32 v186, v165
	v_cvt_f32_f16_sdwa v187, v165 dst_sel:DWORD dst_unused:UNUSED_PAD src0_sel:WORD_1
	ds_write_b128 v4, v[184:187] offset:16384
	s_waitcnt vmcnt(4)
	v_cvt_f32_f16_e32 v188, v166
	v_cvt_f32_f16_sdwa v189, v166 dst_sel:DWORD dst_unused:UNUSED_PAD src0_sel:WORD_1
	v_cvt_f32_f16_e32 v190, v167
	v_cvt_f32_f16_sdwa v191, v167 dst_sel:DWORD dst_unused:UNUSED_PAD src0_sel:WORD_1
	ds_write_b128 v4, v[188:191] offset:24576
	s_waitcnt vmcnt(3)
	v_cvt_f32_f16_e32 v192, v168
	v_cvt_f32_f16_sdwa v193, v168 dst_sel:DWORD dst_unused:UNUSED_PAD src0_sel:WORD_1
	v_cvt_f32_f16_e32 v194, v169
	v_cvt_f32_f16_sdwa v195, v169 dst_sel:DWORD dst_unused:UNUSED_PAD src0_sel:WORD_1
	ds_write_b128 v4, v[192:195] offset:32768
	s_waitcnt vmcnt(2)
	v_cvt_f32_f16_e32 v196, v170
	v_cvt_f32_f16_sdwa v197, v170 dst_sel:DWORD dst_unused:UNUSED_PAD src0_sel:WORD_1
	v_cvt_f32_f16_e32 v198, v171
	v_cvt_f32_f16_sdwa v199, v171 dst_sel:DWORD dst_unused:UNUSED_PAD src0_sel:WORD_1
	ds_write_b128 v4, v[196:199] offset:40960
	s_waitcnt vmcnt(1)
	v_cvt_f32_f16_e32 v200, v172
	v_cvt_f32_f16_sdwa v201, v172 dst_sel:DWORD dst_unused:UNUSED_PAD src0_sel:WORD_1
	v_cvt_f32_f16_e32 v202, v173
	v_cvt_f32_f16_sdwa v203, v173 dst_sel:DWORD dst_unused:UNUSED_PAD src0_sel:WORD_1
	ds_write_b128 v4, v[200:203] offset:49152
	s_waitcnt vmcnt(0)
	v_cvt_f32_f16_e32 v204, v174
	v_cvt_f32_f16_sdwa v205, v174 dst_sel:DWORD dst_unused:UNUSED_PAD src0_sel:WORD_1
	v_cvt_f32_f16_e32 v206, v175
	v_cvt_f32_f16_sdwa v207, v175 dst_sel:DWORD dst_unused:UNUSED_PAD src0_sel:WORD_1
	ds_write_b128 v4, v[204:207] offset:57344

.LBB0_1032:
	v_ashrrev_i32_e32 v6, 6, v1
	v_add_u32_e32 v2, s80, v6
	v_ashrrev_i32_e32 v3, 31, v2
	v_and_b32_e32 v7, 0xfc, v0
	v_lshlrev_b64 v[2:3], 9, v[2:3]
	v_lshlrev_b32_e32 v68, 1, v7
	v_lshl_add_u64 v[2:3], s[46:47], 0, v[2:3]
	v_lshl_add_u64 v[2:3], v[2:3], 0, v[68:69]
	v_lshlrev_b32_e32 v6, 10, v6
	v_lshlrev_b32_e32 v7, 2, v7
	v_add3_u32 v6, 0, v6, v7
	s_mov_b64 s[8:9], 0x1000
	global_load_dwordx2 v[160:161], v[2:3], off
	v_lshl_add_u64 v[2:3], v[2:3], 0, s[8:9]
	global_load_dwordx2 v[162:163], v[2:3], off
	v_lshl_add_u64 v[2:3], v[2:3], 0, s[8:9]
	global_load_dwordx2 v[164:165], v[2:3], off
	v_lshl_add_u64 v[2:3], v[2:3], 0, s[8:9]
	global_load_dwordx2 v[166:167], v[2:3], off
	v_lshl_add_u64 v[2:3], v[2:3], 0, s[8:9]
	global_load_dwordx2 v[168:169], v[2:3], off
	v_lshl_add_u64 v[2:3], v[2:3], 0, s[8:9]
	global_load_dwordx2 v[170:171], v[2:3], off
	v_lshl_add_u64 v[2:3], v[2:3], 0, s[8:9]
	global_load_dwordx2 v[172:173], v[2:3], off
	v_lshl_add_u64 v[2:3], v[2:3], 0, s[8:9]
	global_load_dwordx2 v[174:175], v[2:3], off
	s_waitcnt vmcnt(7)
	v_cvt_f32_f16_e32 v176, v160
	v_cvt_f32_f16_sdwa v177, v160 dst_sel:DWORD dst_unused:UNUSED_PAD src0_sel:WORD_1
	v_cvt_f32_f16_e32 v178, v161
	v_cvt_f32_f16_sdwa v179, v161 dst_sel:DWORD dst_unused:UNUSED_PAD src0_sel:WORD_1
	ds_write_b128 v6, v[176:179]
	s_waitcnt vmcnt(6)
	v_cvt_f32_f16_e32 v180, v162
	v_cvt_f32_f16_sdwa v181, v162 dst_sel:DWORD dst_unused:UNUSED_PAD src0_sel:WORD_1
	v_cvt_f32_f16_e32 v182, v163
	v_cvt_f32_f16_sdwa v183, v163 dst_sel:DWORD dst_unused:UNUSED_PAD src0_sel:WORD_1
	ds_write_b128 v6, v[180:183] offset:8192
	s_waitcnt vmcnt(5)
	v_cvt_f32_f16_e32 v184, v164
	v_cvt_f32_f16_sdwa v185, v164 dst_sel:DWORD dst_unused:UNUSED_PAD src0_sel:WORD_1
	v_cvt_f32_f16_e32 v186, v165
	v_cvt_f32_f16_sdwa v187, v165 dst_sel:DWORD dst_unused:UNUSED_PAD src0_sel:WORD_1
	ds_write_b128 v6, v[184:187] offset:16384
	s_waitcnt vmcnt(4)
	v_cvt_f32_f16_e32 v188, v166
	v_cvt_f32_f16_sdwa v189, v166 dst_sel:DWORD dst_unused:UNUSED_PAD src0_sel:WORD_1
	v_cvt_f32_f16_e32 v190, v167
	v_cvt_f32_f16_sdwa v191, v167 dst_sel:DWORD dst_unused:UNUSED_PAD src0_sel:WORD_1
	ds_write_b128 v6, v[188:191] offset:24576
	s_waitcnt vmcnt(3)
	v_cvt_f32_f16_e32 v192, v168
	v_cvt_f32_f16_sdwa v193, v168 dst_sel:DWORD dst_unused:UNUSED_PAD src0_sel:WORD_1
	v_cvt_f32_f16_e32 v194, v169
	v_cvt_f32_f16_sdwa v195, v169 dst_sel:DWORD dst_unused:UNUSED_PAD src0_sel:WORD_1
	ds_write_b128 v6, v[192:195] offset:32768
	s_waitcnt vmcnt(2)
	v_cvt_f32_f16_e32 v196, v170
	v_cvt_f32_f16_sdwa v197, v170 dst_sel:DWORD dst_unused:UNUSED_PAD src0_sel:WORD_1
	v_cvt_f32_f16_e32 v198, v171
	v_cvt_f32_f16_sdwa v199, v171 dst_sel:DWORD dst_unused:UNUSED_PAD src0_sel:WORD_1
	ds_write_b128 v6, v[196:199] offset:40960
	s_waitcnt vmcnt(1)
	v_cvt_f32_f16_e32 v200, v172
	v_cvt_f32_f16_sdwa v201, v172 dst_sel:DWORD dst_unused:UNUSED_PAD src0_sel:WORD_1
	v_cvt_f32_f16_e32 v202, v173
	v_cvt_f32_f16_sdwa v203, v173 dst_sel:DWORD dst_unused:UNUSED_PAD src0_sel:WORD_1
	ds_write_b128 v6, v[200:203] offset:49152
	s_waitcnt vmcnt(0)
	v_cvt_f32_f16_e32 v204, v174
	v_cvt_f32_f16_sdwa v205, v174 dst_sel:DWORD dst_unused:UNUSED_PAD src0_sel:WORD_1
	v_cvt_f32_f16_e32 v206, v175
	v_cvt_f32_f16_sdwa v207, v175 dst_sel:DWORD dst_unused:UNUSED_PAD src0_sel:WORD_1
	ds_write_b128 v6, v[204:207] offset:57344

.LBB0_2203:
	v_ashrrev_i32_e32 v29, 6, v27
	v_add_u32_e32 v30, s18, v29
	v_ashrrev_i32_e32 v31, 31, v30
	v_and_b32_e32 v34, 0xfc, v1
	v_lshlrev_b64 v[30:31], 9, v[30:31]
	v_lshlrev_b32_e32 v4, 1, v34
	v_lshl_add_u64 v[30:31], s[28:29], 0, v[30:31]
	v_lshl_add_u64 v[30:31], v[30:31], 0, v[4:5]
	v_lshlrev_b32_e32 v29, 10, v29
	v_lshlrev_b32_e32 v34, 2, v34
	v_add3_u32 v4, 0, v29, v34
	s_mov_b64 s[12:13], 0x1000
	global_load_dwordx2 v[160:161], v[30:31], off
	v_lshl_add_u64 v[30:31], v[30:31], 0, s[12:13]
	global_load_dwordx2 v[162:163], v[30:31], off
	v_lshl_add_u64 v[30:31], v[30:31], 0, s[12:13]
	global_load_dwordx2 v[164:165], v[30:31], off
	v_lshl_add_u64 v[30:31], v[30:31], 0, s[12:13]
	global_load_dwordx2 v[166:167], v[30:31], off
	v_lshl_add_u64 v[30:31], v[30:31], 0, s[12:13]
	global_load_dwordx2 v[168:169], v[30:31], off
	v_lshl_add_u64 v[30:31], v[30:31], 0, s[12:13]
	global_load_dwordx2 v[170:171], v[30:31], off
	v_lshl_add_u64 v[30:31], v[30:31], 0, s[12:13]
	global_load_dwordx2 v[172:173], v[30:31], off
	v_lshl_add_u64 v[30:31], v[30:31], 0, s[12:13]
	global_load_dwordx2 v[174:175], v[30:31], off
	s_waitcnt vmcnt(7)
	v_cvt_f32_f16_e32 v176, v160
	v_cvt_f32_f16_sdwa v177, v160 dst_sel:DWORD dst_unused:UNUSED_PAD src0_sel:WORD_1
	v_cvt_f32_f16_e32 v178, v161
	v_cvt_f32_f16_sdwa v179, v161 dst_sel:DWORD dst_unused:UNUSED_PAD src0_sel:WORD_1
	ds_write_b128 v4, v[176:179]
	s_waitcnt vmcnt(6)
	v_cvt_f32_f16_e32 v180, v162
	v_cvt_f32_f16_sdwa v181, v162 dst_sel:DWORD dst_unused:UNUSED_PAD src0_sel:WORD_1
	v_cvt_f32_f16_e32 v182, v163
	v_cvt_f32_f16_sdwa v183, v163 dst_sel:DWORD dst_unused:UNUSED_PAD src0_sel:WORD_1
	ds_write_b128 v4, v[180:183] offset:8192
	s_waitcnt vmcnt(5)
	v_cvt_f32_f16_e32 v184, v164
	v_cvt_f32_f16_sdwa v185, v164 dst_sel:DWORD dst_unused:UNUSED_PAD src0_sel:WORD_1
	v_cvt_f32_f16_e32 v186, v165
	v_cvt_f32_f16_sdwa v187, v165 dst_sel:DWORD dst_unused:UNUSED_PAD src0_sel:WORD_1
	ds_write_b128 v4, v[184:187] offset:16384
	s_waitcnt vmcnt(4)
	v_cvt_f32_f16_e32 v188, v166
	v_cvt_f32_f16_sdwa v189, v166 dst_sel:DWORD dst_unused:UNUSED_PAD src0_sel:WORD_1
	v_cvt_f32_f16_e32 v190, v167
	v_cvt_f32_f16_sdwa v191, v167 dst_sel:DWORD dst_unused:UNUSED_PAD src0_sel:WORD_1
	ds_write_b128 v4, v[188:191] offset:24576
	s_waitcnt vmcnt(3)
	v_cvt_f32_f16_e32 v192, v168
	v_cvt_f32_f16_sdwa v193, v168 dst_sel:DWORD dst_unused:UNUSED_PAD src0_sel:WORD_1
	v_cvt_f32_f16_e32 v194, v169
	v_cvt_f32_f16_sdwa v195, v169 dst_sel:DWORD dst_unused:UNUSED_PAD src0_sel:WORD_1
	ds_write_b128 v4, v[192:195] offset:32768
	s_waitcnt vmcnt(2)
	v_cvt_f32_f16_e32 v196, v170
	v_cvt_f32_f16_sdwa v197, v170 dst_sel:DWORD dst_unused:UNUSED_PAD src0_sel:WORD_1
	v_cvt_f32_f16_e32 v198, v171
	v_cvt_f32_f16_sdwa v199, v171 dst_sel:DWORD dst_unused:UNUSED_PAD src0_sel:WORD_1
	ds_write_b128 v4, v[196:199] offset:40960
	s_waitcnt vmcnt(1)
	v_cvt_f32_f16_e32 v200, v172
	v_cvt_f32_f16_sdwa v201, v172 dst_sel:DWORD dst_unused:UNUSED_PAD src0_sel:WORD_1
	v_cvt_f32_f16_e32 v202, v173
	v_cvt_f32_f16_sdwa v203, v173 dst_sel:DWORD dst_unused:UNUSED_PAD src0_sel:WORD_1
	ds_write_b128 v4, v[200:203] offset:49152
	s_waitcnt vmcnt(0)
	v_cvt_f32_f16_e32 v204, v174
	v_cvt_f32_f16_sdwa v205, v174 dst_sel:DWORD dst_unused:UNUSED_PAD src0_sel:WORD_1
	v_cvt_f32_f16_e32 v206, v175
	v_cvt_f32_f16_sdwa v207, v175 dst_sel:DWORD dst_unused:UNUSED_PAD src0_sel:WORD_1
	ds_write_b128 v4, v[204:207] offset:57344
